# weight-conversion items with per-row gains (FFN2-in, input-projection weights): the 8 row loads and 8 gain loads of an item issued together, one wait
# speedup vs baseline: 1.0021x; 1.0021x over previous
; #define LAS __attribute__((address_space(3)))
; __device__ __forceinline__ void transpose_tile_block(int kind, const float* W, int N, int K, int ND, bf16* WT, const float* gk, int item, LAS unsigned char* lds, int tid) {
;     ...
;     __syncthreads();
; #pragma unroll
;     for (int r = 0; r < 8; ++r) { const int id = tid + NTHREADS * r, row = id >> 6, cv = id & 63, col = cv * 4;
;         f32x4 v = (f32x4){0.f, 0.f, 0.f, 0.f};
;         if (col < nvalid) { const int src = (col < 128) ? srcA + col : srcB + (col - 128); v = *(const f32x4*)(W + (size_t)(k0 + row) * N + src); }
;         const float g = (gk ? gk[k0 + row] : 1.0f) * cs;
;         *(LAS f32x4*)(T + row * LP + col) = v * g; }
.LBB0_114:
	s_andn2_b64 vcc, exec, s[8:9]
	s_cbranch_vccnz .LBB0_132
	s_add_i32 s20, s29, 0xfc80
	s_and_b32 s22, s20, 0xffff
	s_mov_b64 s[8:9], s[90:91]
	s_mul_i32 s22, s22, 0xba2f
	s_lshr_b32 s22, s22, 20
	s_load_dwordx2 s[8:9], s[8:9], 0x90
	s_mul_i32 s23, s22, 22
	s_sub_i32 s20, s20, s23
	s_and_b32 s24, s20, 0xffff
	s_lshl_b32 s20, s22, 6
	s_lshl_b32 s22, s24, 7
	v_add_lshl_u32 v16, s22, v53, 2
	s_mov_b64 s[10:11], s[90:91]
	s_waitcnt lgkmcnt(0)
	v_lshl_add_u64 v[32:33], s[8:9], 0, v[16:17]
	v_add_u32_e32 v2, s20, v36
	v_mad_i64_i32 v[4:5], s[8:9], v2, s19, v[32:33]
	s_load_dwordx2 s[10:11], s[10:11], 0x88
	s_waitcnt vmcnt(0) lgkmcnt(0)
	s_barrier
	v_add_u32_e32 v120, s20, v36
	v_add_u32_e32 v121, s20, v37
	v_add_u32_e32 v122, s20, v38
	v_add_u32_e32 v123, s20, v39
	v_add_u32_e32 v124, s20, v40
	v_add_u32_e32 v125, s20, v41
	v_add_u32_e32 v126, s20, v42
	v_add_u32_e32 v127, s20, v43
	v_mad_i64_i32 v[128:129], s[22:23], v120, s19, v[32:33]
	global_load_dwordx4 v[88:91], v[128:129], off
	v_mad_i64_i32 v[128:129], s[22:23], v121, s19, v[32:33]
	global_load_dwordx4 v[92:95], v[128:129], off
	v_mad_i64_i32 v[128:129], s[22:23], v122, s19, v[32:33]
	global_load_dwordx4 v[96:99], v[128:129], off
	v_mad_i64_i32 v[128:129], s[22:23], v123, s19, v[32:33]
	global_load_dwordx4 v[100:103], v[128:129], off
	v_mad_i64_i32 v[128:129], s[22:23], v124, s19, v[32:33]
	global_load_dwordx4 v[104:107], v[128:129], off
	v_mad_i64_i32 v[128:129], s[22:23], v125, s19, v[32:33]
	global_load_dwordx4 v[108:111], v[128:129], off
	v_mad_i64_i32 v[128:129], s[22:23], v126, s19, v[32:33]
	global_load_dwordx4 v[112:115], v[128:129], off
	v_mad_i64_i32 v[128:129], s[22:23], v127, s19, v[32:33]
	global_load_dwordx4 v[116:119], v[128:129], off
	s_cmp_eq_u64 s[10:11], 0
	s_cbranch_scc1 .Lcvk1_none
	v_mov_b32_e32 v86, v120
	v_ashrrev_i32_e32 v87, 31, v86
	v_lshl_add_u64 v[130:131], v[86:87], 2, s[10:11]
	global_load_dword v120, v[130:131], off
	v_mov_b32_e32 v86, v121
	v_ashrrev_i32_e32 v87, 31, v86
	v_lshl_add_u64 v[130:131], v[86:87], 2, s[10:11]
	global_load_dword v121, v[130:131], off
	v_mov_b32_e32 v86, v122
	v_ashrrev_i32_e32 v87, 31, v86
	v_lshl_add_u64 v[130:131], v[86:87], 2, s[10:11]
	global_load_dword v122, v[130:131], off
	v_mov_b32_e32 v86, v123
	v_ashrrev_i32_e32 v87, 31, v86
	v_lshl_add_u64 v[130:131], v[86:87], 2, s[10:11]
	global_load_dword v123, v[130:131], off
	v_mov_b32_e32 v86, v124
	v_ashrrev_i32_e32 v87, 31, v86
	v_lshl_add_u64 v[130:131], v[86:87], 2, s[10:11]
	global_load_dword v124, v[130:131], off
	v_mov_b32_e32 v86, v125
	v_ashrrev_i32_e32 v87, 31, v86
	v_lshl_add_u64 v[130:131], v[86:87], 2, s[10:11]
	global_load_dword v125, v[130:131], off
	v_mov_b32_e32 v86, v126
	v_ashrrev_i32_e32 v87, 31, v86
	v_lshl_add_u64 v[130:131], v[86:87], 2, s[10:11]
	global_load_dword v126, v[130:131], off
	v_mov_b32_e32 v86, v127
	v_ashrrev_i32_e32 v87, 31, v86
	v_lshl_add_u64 v[130:131], v[86:87], 2, s[10:11]
	global_load_dword v127, v[130:131], off
	s_branch .Lcvk1_go
.Lcvk1_none:
	v_mov_b32_e32 v120, 1.0
	v_mov_b32_e32 v121, 1.0
	v_mov_b32_e32 v122, 1.0
	v_mov_b32_e32 v123, 1.0
	v_mov_b32_e32 v124, 1.0
	v_mov_b32_e32 v125, 1.0
	v_mov_b32_e32 v126, 1.0
	v_mov_b32_e32 v127, 1.0
; #define LAS __attribute__((address_space(3)))
; __device__ __forceinline__ unsigned pk2(float lo, float hi) { return pg8::cvt_pk_bf16(lo, hi); }
; __device__ __forceinline__ void transpose_tile_block(int kind, const float* W, int N, int K, int ND, bf16* WT, const float* gk, int item, LAS unsigned char* lds, int tid) {
;     ...
;     for (int r = 0; r < 8; ++r) { const int id = tid + NTHREADS * r, row = id >> 6, cv = id & 63, col = cv * 4;
;         f32x4 v = (f32x4){0.f, 0.f, 0.f, 0.f};
;         if (col < nvalid) { const int src = (col < 128) ? srcA + col : srcB + (col - 128); v = *(const f32x4*)(W + (size_t)(k0 + row) * N + src); }
;         const float g = (gk ? gk[k0 + row] : 1.0f) * cs;
;         *(LAS f32x4*)(T + row * LP + col) = v * g; }
;     __syncthreads();
; #pragma unroll
;     for (int r = 0; r < 4; ++r) { const int id = tid + NTHREADS * r, n = id >> 3, k8 = id & 7; const LAS float* s = T + (k8 * 8) * LP + n;
;         u32x4 o; o.x = pk2(s[0 * LP], s[1 * LP]); o.y = pk2(s[2 * LP], s[3 * LP]); o.z = pk2(s[4 * LP], s[5 * LP]); o.w = pk2(s[6 * LP], s[7 * LP]);
;         *(u32x4*)(WT + (size_t)(drow0 + n) * K + k0 + 8 * k8) = o; }
.Lcvk1_go:
	s_waitcnt vmcnt(0)
	v_mul_f32_e32 v88, v88, v120
	v_mul_f32_e32 v89, v89, v120
	v_mul_f32_e32 v90, v90, v120
	v_mul_f32_e32 v91, v91, v120
	ds_write_b128 v54, v[88:91]
	v_mul_f32_e32 v92, v92, v121
	v_mul_f32_e32 v93, v93, v121
	v_mul_f32_e32 v94, v94, v121
	v_mul_f32_e32 v95, v95, v121
	ds_write_b128 v55, v[92:95]
	v_mul_f32_e32 v96, v96, v122
	v_mul_f32_e32 v97, v97, v122
	v_mul_f32_e32 v98, v98, v122
	v_mul_f32_e32 v99, v99, v122
	ds_write_b128 v56, v[96:99]
	v_mul_f32_e32 v100, v100, v123
	v_mul_f32_e32 v101, v101, v123
	v_mul_f32_e32 v102, v102, v123
	v_mul_f32_e32 v103, v103, v123
	ds_write_b128 v57, v[100:103]
	v_mul_f32_e32 v104, v104, v124
	v_mul_f32_e32 v105, v105, v124
	v_mul_f32_e32 v106, v106, v124
	v_mul_f32_e32 v107, v107, v124
	ds_write_b128 v58, v[104:107]
	v_mul_f32_e32 v108, v108, v125
	v_mul_f32_e32 v109, v109, v125
	v_mul_f32_e32 v110, v110, v125
	v_mul_f32_e32 v111, v111, v125
	ds_write_b128 v59, v[108:111]
	v_mul_f32_e32 v112, v112, v126
	v_mul_f32_e32 v113, v113, v126
	v_mul_f32_e32 v114, v114, v126
	v_mul_f32_e32 v115, v115, v126
	ds_write_b128 v60, v[112:115]
	v_mul_f32_e32 v116, v116, v127
	v_mul_f32_e32 v117, v117, v127
	v_mul_f32_e32 v118, v118, v127
	v_mul_f32_e32 v119, v119, v127
	ds_write_b128 v61, v[116:119]
	s_waitcnt lgkmcnt(0)
	s_barrier
	ds_read_b32 v2, v45
	ds_read_b32 v3, v45 offset:1040
	ds_read_b32 v4, v45 offset:2080
	ds_read_b32 v5, v45 offset:3120
	ds_read_b32 v8, v45 offset:4160
	ds_read_b32 v9, v45 offset:5200
	ds_read_b32 v10, v45 offset:6240
	ds_read_b32 v11, v45 offset:7280
	s_lshl_b32 s8, s24, 8
	s_waitcnt lgkmcnt(6)
	v_cvt_pk_bf16_f32 v2, v2, v3
	s_waitcnt lgkmcnt(4)
	v_cvt_pk_bf16_f32 v3, v4, v5
	s_waitcnt lgkmcnt(2)
	v_cvt_pk_bf16_f32 v4, v8, v9
	s_waitcnt lgkmcnt(0)
	v_cvt_pk_bf16_f32 v5, v10, v11
	v_add_u32_e32 v8, s8, v44
	ds_read_b32 v10, v47
	ds_read_b32 v11, v47 offset:1040
	ds_read_b32 v12, v47 offset:2080
	ds_read_b32 v13, v47 offset:3120
	ds_read_b32 v16, v47 offset:4160
	ds_read_b32 v32, v47 offset:5200
	ds_read_b32 v33, v47 offset:6240
	ds_read_b32 v34, v47 offset:7280
	s_lshl_b32 s20, s20, 1
	v_ashrrev_i32_e32 v9, 31, v8
	v_lshl_add_u64 v[6:7], v[20:21], 0, s[20:21]
	v_lshlrev_b64 v[8:9], 11, v[8:9]
	v_lshl_add_u64 v[8:9], v[6:7], 0, v[8:9]
	global_store_dwordx4 v[8:9], v[2:5], off
	v_add_u32_e32 v8, s8, v46
	v_ashrrev_i32_e32 v9, 31, v8
	s_waitcnt lgkmcnt(6)
	v_cvt_pk_bf16_f32 v2, v10, v11
	s_waitcnt lgkmcnt(4)
	v_cvt_pk_bf16_f32 v3, v12, v13
	s_waitcnt lgkmcnt(2)
	v_cvt_pk_bf16_f32 v4, v16, v32
	s_waitcnt lgkmcnt(0)
	v_cvt_pk_bf16_f32 v5, v33, v34
	ds_read_b32 v10, v49
	ds_read_b32 v11, v49 offset:1040
	ds_read_b32 v12, v49 offset:2080
	ds_read_b32 v13, v49 offset:3120
	ds_read_b32 v16, v49 offset:4160
	ds_read_b32 v32, v49 offset:5200
	ds_read_b32 v33, v49 offset:6240
	ds_read_b32 v34, v49 offset:7280
	v_lshlrev_b64 v[8:9], 11, v[8:9]
	v_lshl_add_u64 v[8:9], v[6:7], 0, v[8:9]
	global_store_dwordx4 v[8:9], v[2:5], off
	v_add_u32_e32 v8, s8, v48
	v_ashrrev_i32_e32 v9, 31, v8
	s_waitcnt lgkmcnt(6)
	v_cvt_pk_bf16_f32 v2, v10, v11
	s_waitcnt lgkmcnt(4)
	v_cvt_pk_bf16_f32 v3, v12, v13
	s_waitcnt lgkmcnt(2)
	v_cvt_pk_bf16_f32 v4, v16, v32
	s_waitcnt lgkmcnt(0)
	v_cvt_pk_bf16_f32 v5, v33, v34
	v_lshlrev_b64 v[8:9], 11, v[8:9]
	ds_read_b32 v10, v51
	ds_read_b32 v11, v51 offset:1040
	ds_read_b32 v12, v51 offset:2080
	ds_read_b32 v13, v51 offset:3120
	ds_read_b32 v16, v51 offset:4160
	ds_read_b32 v32, v51 offset:5200
	ds_read_b32 v33, v51 offset:6240
	ds_read_b32 v34, v51 offset:7280
	v_lshl_add_u64 v[8:9], v[6:7], 0, v[8:9]
	global_store_dwordx4 v[8:9], v[2:5], off
	v_add_u32_e32 v8, s8, v50
	v_ashrrev_i32_e32 v9, 31, v8
	v_lshlrev_b64 v[8:9], 11, v[8:9]
	s_waitcnt lgkmcnt(6)
	v_cvt_pk_bf16_f32 v2, v10, v11
	s_waitcnt lgkmcnt(4)
	v_cvt_pk_bf16_f32 v3, v12, v13
	s_waitcnt lgkmcnt(2)
	v_cvt_pk_bf16_f32 v4, v16, v32
	s_waitcnt lgkmcnt(0)
	v_cvt_pk_bf16_f32 v5, v33, v34
	v_lshl_add_u64 v[6:7], v[6:7], 0, v[8:9]
	global_store_dwordx4 v[6:7], v[2:5], off

; #define LAS __attribute__((address_space(3)))
; __device__ __forceinline__ void transpose_tile_block(int kind, const float* W, int N, int K, int ND, bf16* WT, const float* gk, int item, LAS unsigned char* lds, int tid) {
;     ...
;     __syncthreads();
; #pragma unroll
;     for (int r = 0; r < 8; ++r) { const int id = tid + NTHREADS * r, row = id >> 6, cv = id & 63, col = cv * 4;
;         f32x4 v = (f32x4){0.f, 0.f, 0.f, 0.f};
;         if (col < nvalid) { const int src = (col < 128) ? srcA + col : srcB + (col - 128); v = *(const f32x4*)(W + (size_t)(k0 + row) * N + src); }
;         const float g = (gk ? gk[k0 + row] : 1.0f) * cs;
;         *(LAS f32x4*)(T + row * LP + col) = v * g; }
.LBB0_148:
	s_and_b32 s8, 0xffff, s20
	v_add_u32_e32 v2, s34, v15
	v_add_u32_e32 v3, s31, v52
	s_lshl_b32 s20, s8, 6
	v_cndmask_b32_e64 v16, v3, v2, s[6:7]
	v_cmp_gt_u32_e64 s[8:9], s35, v15
	s_waitcnt lgkmcnt(0)
	v_lshl_add_u64 v[6:7], v[16:17], 2, s[24:25]
	v_mov_b32_e32 v2, 0
	v_add_u32_e32 v8, s20, v36
	v_mov_b32_e32 v3, 0
	v_mov_b32_e32 v4, 0
	v_mov_b32_e32 v5, 0
	s_waitcnt vmcnt(0)
	s_barrier
	v_mov_b32_e32 v88, 0
	v_mov_b32_e32 v89, 0
	v_mov_b32_e32 v90, 0
	v_mov_b32_e32 v91, 0
	v_mov_b32_e32 v92, 0
	v_mov_b32_e32 v93, 0
	v_mov_b32_e32 v94, 0
	v_mov_b32_e32 v95, 0
	v_mov_b32_e32 v96, 0
	v_mov_b32_e32 v97, 0
	v_mov_b32_e32 v98, 0
	v_mov_b32_e32 v99, 0
	v_mov_b32_e32 v100, 0
	v_mov_b32_e32 v101, 0
	v_mov_b32_e32 v102, 0
	v_mov_b32_e32 v103, 0
	v_mov_b32_e32 v104, 0
	v_mov_b32_e32 v105, 0
	v_mov_b32_e32 v106, 0
	v_mov_b32_e32 v107, 0
	v_mov_b32_e32 v108, 0
	v_mov_b32_e32 v109, 0
	v_mov_b32_e32 v110, 0
	v_mov_b32_e32 v111, 0
	v_mov_b32_e32 v112, 0
	v_mov_b32_e32 v113, 0
	v_mov_b32_e32 v114, 0
	v_mov_b32_e32 v115, 0
	v_mov_b32_e32 v116, 0
	v_mov_b32_e32 v117, 0
	v_mov_b32_e32 v118, 0
	v_mov_b32_e32 v119, 0
	v_add_u32_e32 v120, s20, v36
	v_add_u32_e32 v121, s20, v37
	v_add_u32_e32 v122, s20, v38
	v_add_u32_e32 v123, s20, v39
	v_add_u32_e32 v124, s20, v40
	v_add_u32_e32 v125, s20, v41
	v_add_u32_e32 v126, s20, v42
	v_add_u32_e32 v127, s20, v43
	s_and_saveexec_b64 s[10:11], s[8:9]
	v_mad_i64_i32 v[128:129], s[24:25], v120, s28, v[6:7]
	global_load_dwordx4 v[88:91], v[128:129], off
	v_mad_i64_i32 v[128:129], s[24:25], v121, s28, v[6:7]
	global_load_dwordx4 v[92:95], v[128:129], off
	v_mad_i64_i32 v[128:129], s[24:25], v122, s28, v[6:7]
	global_load_dwordx4 v[96:99], v[128:129], off
	v_mad_i64_i32 v[128:129], s[24:25], v123, s28, v[6:7]
	global_load_dwordx4 v[100:103], v[128:129], off
	v_mad_i64_i32 v[128:129], s[24:25], v124, s28, v[6:7]
	global_load_dwordx4 v[104:107], v[128:129], off
	v_mad_i64_i32 v[128:129], s[24:25], v125, s28, v[6:7]
	global_load_dwordx4 v[108:111], v[128:129], off
	v_mad_i64_i32 v[128:129], s[24:25], v126, s28, v[6:7]
	global_load_dwordx4 v[112:115], v[128:129], off
	v_mad_i64_i32 v[128:129], s[24:25], v127, s28, v[6:7]
	global_load_dwordx4 v[116:119], v[128:129], off
	s_mov_b64 exec, s[10:11]
	s_cmp_eq_u64 s[22:23], 0
	s_cbranch_scc1 .Lcvk2_none
	v_mov_b32_e32 v86, v120
	v_ashrrev_i32_e32 v87, 31, v86
	v_lshl_add_u64 v[130:131], v[86:87], 2, s[22:23]
	global_load_dword v120, v[130:131], off
	v_mov_b32_e32 v86, v121
	v_ashrrev_i32_e32 v87, 31, v86
	v_lshl_add_u64 v[130:131], v[86:87], 2, s[22:23]
	global_load_dword v121, v[130:131], off
	v_mov_b32_e32 v86, v122
	v_ashrrev_i32_e32 v87, 31, v86
	v_lshl_add_u64 v[130:131], v[86:87], 2, s[22:23]
	global_load_dword v122, v[130:131], off
	v_mov_b32_e32 v86, v123
	v_ashrrev_i32_e32 v87, 31, v86
	v_lshl_add_u64 v[130:131], v[86:87], 2, s[22:23]
	global_load_dword v123, v[130:131], off
	v_mov_b32_e32 v86, v124
	v_ashrrev_i32_e32 v87, 31, v86
	v_lshl_add_u64 v[130:131], v[86:87], 2, s[22:23]
	global_load_dword v124, v[130:131], off
	v_mov_b32_e32 v86, v125
	v_ashrrev_i32_e32 v87, 31, v86
	v_lshl_add_u64 v[130:131], v[86:87], 2, s[22:23]
	global_load_dword v125, v[130:131], off
	v_mov_b32_e32 v86, v126
	v_ashrrev_i32_e32 v87, 31, v86
	v_lshl_add_u64 v[130:131], v[86:87], 2, s[22:23]
	global_load_dword v126, v[130:131], off
	v_mov_b32_e32 v86, v127
	v_ashrrev_i32_e32 v87, 31, v86
	v_lshl_add_u64 v[130:131], v[86:87], 2, s[22:23]
	global_load_dword v127, v[130:131], off
	s_branch .Lcvk2_go

; #define LAS __attribute__((address_space(3)))
; __device__ __forceinline__ unsigned pk2(float lo, float hi) { return pg8::cvt_pk_bf16(lo, hi); }
; __device__ __forceinline__ void transpose_tile_block(int kind, const float* W, int N, int K, int ND, bf16* WT, const float* gk, int item, LAS unsigned char* lds, int tid) {
;     ...
;     for (int r = 0; r < 8; ++r) { const int id = tid + NTHREADS * r, row = id >> 6, cv = id & 63, col = cv * 4;
;         f32x4 v = (f32x4){0.f, 0.f, 0.f, 0.f};
;         if (col < nvalid) { const int src = (col < 128) ? srcA + col : srcB + (col - 128); v = *(const f32x4*)(W + (size_t)(k0 + row) * N + src); }
;         const float g = (gk ? gk[k0 + row] : 1.0f) * cs;
;         *(LAS f32x4*)(T + row * LP + col) = v * g; }
;     __syncthreads();
; #pragma unroll
;     for (int r = 0; r < 4; ++r) { const int id = tid + NTHREADS * r, n = id >> 3, k8 = id & 7; const LAS float* s = T + (k8 * 8) * LP + n;
;         u32x4 o; o.x = pk2(s[0 * LP], s[1 * LP]); o.y = pk2(s[2 * LP], s[3 * LP]); o.z = pk2(s[4 * LP], s[5 * LP]); o.w = pk2(s[6 * LP], s[7 * LP]);
;         *(u32x4*)(WT + (size_t)(drow0 + n) * K + k0 + 8 * k8) = o; }
.Lcvk2_go:
	s_waitcnt vmcnt(0)
	v_mul_f32_e32 v120, v10, v120
	v_mul_f32_e32 v88, v88, v120
	v_mul_f32_e32 v89, v89, v120
	v_mul_f32_e32 v90, v90, v120
	v_mul_f32_e32 v91, v91, v120
	ds_write_b128 v54, v[88:91]
	v_mul_f32_e32 v121, v10, v121
	v_mul_f32_e32 v92, v92, v121
	v_mul_f32_e32 v93, v93, v121
	v_mul_f32_e32 v94, v94, v121
	v_mul_f32_e32 v95, v95, v121
	ds_write_b128 v55, v[92:95]
	v_mul_f32_e32 v122, v10, v122
	v_mul_f32_e32 v96, v96, v122
	v_mul_f32_e32 v97, v97, v122
	v_mul_f32_e32 v98, v98, v122
	v_mul_f32_e32 v99, v99, v122
	ds_write_b128 v56, v[96:99]
	v_mul_f32_e32 v123, v10, v123
	v_mul_f32_e32 v100, v100, v123
	v_mul_f32_e32 v101, v101, v123
	v_mul_f32_e32 v102, v102, v123
	v_mul_f32_e32 v103, v103, v123
	ds_write_b128 v57, v[100:103]
	v_mul_f32_e32 v124, v10, v124
	v_mul_f32_e32 v104, v104, v124
	v_mul_f32_e32 v105, v105, v124
	v_mul_f32_e32 v106, v106, v124
	v_mul_f32_e32 v107, v107, v124
	ds_write_b128 v58, v[104:107]
	v_mul_f32_e32 v125, v10, v125
	v_mul_f32_e32 v108, v108, v125
	v_mul_f32_e32 v109, v109, v125
	v_mul_f32_e32 v110, v110, v125
	v_mul_f32_e32 v111, v111, v125
	ds_write_b128 v59, v[108:111]
	v_mul_f32_e32 v126, v10, v126
	v_mul_f32_e32 v112, v112, v126
	v_mul_f32_e32 v113, v113, v126
	v_mul_f32_e32 v114, v114, v126
	v_mul_f32_e32 v115, v115, v126
	ds_write_b128 v60, v[112:115]
	v_mul_f32_e32 v127, v10, v127
	v_mul_f32_e32 v116, v116, v127
	v_mul_f32_e32 v117, v117, v127
	v_mul_f32_e32 v118, v118, v127
	v_mul_f32_e32 v119, v119, v127
	ds_write_b128 v61, v[116:119]
	s_waitcnt lgkmcnt(0)
	s_barrier
	ds_read_b32 v2, v45
	ds_read_b32 v3, v45 offset:1040
	ds_read_b32 v4, v45 offset:2080
	ds_read_b32 v5, v45 offset:3120
	ds_read_b32 v8, v45 offset:4160
	ds_read_b32 v9, v45 offset:5200
	ds_read_b32 v10, v45 offset:6240
	ds_read_b32 v11, v45 offset:7280
	s_waitcnt lgkmcnt(6)
	v_cvt_pk_bf16_f32 v2, v2, v3
	s_waitcnt lgkmcnt(4)
	v_cvt_pk_bf16_f32 v3, v4, v5
	s_waitcnt lgkmcnt(2)
	v_cvt_pk_bf16_f32 v4, v8, v9
	v_add_u32_e32 v8, s30, v44
	s_waitcnt lgkmcnt(0)
	v_cvt_pk_bf16_f32 v5, v10, v11
	ds_read_b32 v10, v47
	ds_read_b32 v11, v47 offset:1040
	ds_read_b32 v12, v47 offset:2080
	ds_read_b32 v13, v47 offset:3120
	ds_read_b32 v16, v47 offset:4160
	ds_read_b32 v32, v47 offset:5200
	ds_read_b32 v33, v47 offset:6240
	ds_read_b32 v34, v47 offset:7280
	s_lshl_b32 s20, s20, 1
	v_ashrrev_i32_e32 v9, 31, v8
	v_lshl_add_u64 v[6:7], v[28:29], 0, s[20:21]
	v_lshlrev_b64 v[8:9], 11, v[8:9]
	v_lshl_add_u64 v[8:9], v[6:7], 0, v[8:9]
	global_store_dwordx4 v[8:9], v[2:5], off
	v_add_u32_e32 v8, s30, v46
	v_ashrrev_i32_e32 v9, 31, v8
	s_waitcnt lgkmcnt(6)
	v_cvt_pk_bf16_f32 v2, v10, v11
	s_waitcnt lgkmcnt(4)
	v_cvt_pk_bf16_f32 v3, v12, v13
	s_waitcnt lgkmcnt(2)
	v_cvt_pk_bf16_f32 v4, v16, v32
	s_waitcnt lgkmcnt(0)
	v_cvt_pk_bf16_f32 v5, v33, v34
	ds_read_b32 v10, v49
	ds_read_b32 v11, v49 offset:1040
	ds_read_b32 v12, v49 offset:2080
	ds_read_b32 v13, v49 offset:3120
	ds_read_b32 v16, v49 offset:4160
	ds_read_b32 v32, v49 offset:5200
	ds_read_b32 v33, v49 offset:6240
	ds_read_b32 v34, v49 offset:7280
	v_lshlrev_b64 v[8:9], 11, v[8:9]
	v_lshl_add_u64 v[8:9], v[6:7], 0, v[8:9]
	global_store_dwordx4 v[8:9], v[2:5], off
	v_add_u32_e32 v8, s30, v48
	v_ashrrev_i32_e32 v9, 31, v8
	s_waitcnt lgkmcnt(6)
	v_cvt_pk_bf16_f32 v2, v10, v11
	s_waitcnt lgkmcnt(4)
	v_cvt_pk_bf16_f32 v3, v12, v13
	s_waitcnt lgkmcnt(2)
	v_cvt_pk_bf16_f32 v4, v16, v32
	s_waitcnt lgkmcnt(0)
	v_cvt_pk_bf16_f32 v5, v33, v34
	v_lshlrev_b64 v[8:9], 11, v[8:9]
	ds_read_b32 v10, v51
	ds_read_b32 v11, v51 offset:1040
	ds_read_b32 v12, v51 offset:2080
	ds_read_b32 v13, v51 offset:3120
	ds_read_b32 v16, v51 offset:4160
	ds_read_b32 v32, v51 offset:5200
	ds_read_b32 v33, v51 offset:6240
	ds_read_b32 v34, v51 offset:7280
	v_lshl_add_u64 v[8:9], v[6:7], 0, v[8:9]
	global_store_dwordx4 v[8:9], v[2:5], off
	v_add_u32_e32 v8, s30, v50
	v_ashrrev_i32_e32 v9, 31, v8
	v_lshlrev_b64 v[8:9], 11, v[8:9]
	s_waitcnt lgkmcnt(6)
	v_cvt_pk_bf16_f32 v2, v10, v11
	s_waitcnt lgkmcnt(4)
	v_cvt_pk_bf16_f32 v3, v12, v13
	s_waitcnt lgkmcnt(2)
	v_cvt_pk_bf16_f32 v4, v16, v32
	s_waitcnt lgkmcnt(0)
	v_cvt_pk_bf16_f32 v5, v33, v34
	v_lshl_add_u64 v[6:7], v[6:7], 0, v[8:9]
	global_store_dwordx4 v[6:7], v[2:5], off

; template <class Epi, class Sched, bool ALIGN_EPI = false, bool SP2 = false>
; __device__ __forceinline__ void gemm_phase(PG8_LAS unsigned char* lds, const Gemm g, const Sched& S, const Epi& E, const int tid_arg) {
;     ...
; #pragma unroll
;         for (int a = 0; a < 2; ++a)
; #pragma unroll
;             for (int b = 0; b < 2; ++b)
; #pragma unroll
;                 for (int m = 0; m < 4; ++m)
; #pragma unroll
;                     for (int n = 0; n < 2; ++n) acc[a][b][m][n] = (f32x4){0.f, 0.f, 0.f, 0.f};
.LBB0_259:
	s_add_u32 s16, s36, 0x100
	v_mov_b32_e32 v2, 0
	s_addc_u32 s31, s37, 0
	s_mov_b32 s56, -2
	s_waitcnt lgkmcnt(0)
	v_mov_b32_e32 v3, v2
	v_mov_b32_e32 v4, v2
	v_mov_b32_e32 v5, v2
	v_mov_b32_e32 v6, v2
	v_mov_b32_e32 v7, v2
	v_mov_b32_e32 v8, v2
	v_mov_b32_e32 v9, v2
	v_mov_b32_e32 v18, v2
	v_mov_b32_e32 v19, v2
	v_mov_b32_e32 v20, v2
	v_mov_b32_e32 v21, v2
	v_mov_b32_e32 v22, v2
	v_mov_b32_e32 v23, v2
	v_mov_b32_e32 v24, v2
	v_mov_b32_e32 v25, v2
	v_mov_b32_e32 v34, v2
	v_mov_b32_e32 v35, v2
	v_mov_b32_e32 v36, v2
	v_mov_b32_e32 v37, v2
	v_mov_b32_e32 v38, v2
	v_mov_b32_e32 v39, v2
	v_mov_b32_e32 v40, v2
	v_mov_b32_e32 v41, v2
	v_mov_b32_e32 v50, v2
	v_mov_b32_e32 v51, v2
	v_mov_b32_e32 v52, v2
	v_mov_b32_e32 v53, v2
	v_mov_b32_e32 v54, v2
	v_mov_b32_e32 v55, v2
	v_mov_b32_e32 v56, v2
	v_mov_b32_e32 v57, v2
	v_mov_b32_e32 v10, v2
	v_mov_b32_e32 v11, v2
	v_mov_b32_e32 v12, v2
	v_mov_b32_e32 v13, v2
	v_mov_b32_e32 v14, v2
	v_mov_b32_e32 v15, v2
	v_mov_b32_e32 v16, v2
	v_mov_b32_e32 v17, v2
	v_mov_b32_e32 v26, v2
	v_mov_b32_e32 v27, v2
	v_mov_b32_e32 v28, v2
	v_mov_b32_e32 v29, v2
	v_mov_b32_e32 v30, v2
	v_mov_b32_e32 v31, v2
	v_mov_b32_e32 v32, v2
	v_mov_b32_e32 v33, v2
	v_mov_b32_e32 v42, v2
	v_mov_b32_e32 v43, v2
	v_mov_b32_e32 v44, v2
	v_mov_b32_e32 v45, v2
	v_mov_b32_e32 v46, v2
	v_mov_b32_e32 v47, v2
	v_mov_b32_e32 v48, v2
	v_mov_b32_e32 v49, v2
	v_mov_b32_e32 v58, v2
	v_mov_b32_e32 v59, v2
	v_mov_b32_e32 v60, v2
	v_mov_b32_e32 v61, v2
	v_mov_b32_e32 v62, v2
	v_mov_b32_e32 v63, v2
	v_mov_b32_e32 v64, v2
	v_mov_b32_e32 v65, v2
	v_mov_b32_e32 v66, v2
	v_mov_b32_e32 v67, v2
	v_mov_b32_e32 v68, v2
	v_mov_b32_e32 v69, v2
	v_mov_b32_e32 v70, v2
	v_mov_b32_e32 v71, v2
	v_mov_b32_e32 v72, v2
	v_mov_b32_e32 v73, v2
	v_mov_b32_e32 v82, v2
	v_mov_b32_e32 v83, v2
	v_mov_b32_e32 v84, v2
	v_mov_b32_e32 v85, v2
	v_mov_b32_e32 v86, v2
	v_mov_b32_e32 v87, v2
	v_mov_b32_e32 v88, v2
	v_mov_b32_e32 v89, v2
	v_mov_b32_e32 v98, v2
	v_mov_b32_e32 v99, v2
	v_mov_b32_e32 v100, v2
	v_mov_b32_e32 v101, v2
	v_mov_b32_e32 v102, v2
	v_mov_b32_e32 v103, v2
	v_mov_b32_e32 v104, v2
	v_mov_b32_e32 v105, v2
	v_mov_b32_e32 v114, v2
	v_mov_b32_e32 v115, v2
	v_mov_b32_e32 v116, v2
	v_mov_b32_e32 v117, v2
	v_mov_b32_e32 v118, v2
	v_mov_b32_e32 v119, v2
	v_mov_b32_e32 v120, v2
	v_mov_b32_e32 v121, v2
	v_mov_b32_e32 v74, v2
	v_mov_b32_e32 v75, v2
	v_mov_b32_e32 v76, v2
	v_mov_b32_e32 v77, v2
	v_mov_b32_e32 v78, v2
	v_mov_b32_e32 v79, v2
	v_mov_b32_e32 v80, v2
	v_mov_b32_e32 v81, v2
	v_mov_b32_e32 v90, v2
	v_mov_b32_e32 v91, v2
	v_mov_b32_e32 v92, v2
	v_mov_b32_e32 v93, v2
	v_mov_b32_e32 v94, v2
	v_mov_b32_e32 v95, v2
	v_mov_b32_e32 v96, v2
	v_mov_b32_e32 v97, v2
	v_mov_b32_e32 v106, v2
	v_mov_b32_e32 v107, v2
	v_mov_b32_e32 v108, v2
	v_mov_b32_e32 v109, v2
	v_mov_b32_e32 v110, v2
	v_mov_b32_e32 v111, v2
	v_mov_b32_e32 v112, v2
	v_mov_b32_e32 v113, v2
	v_mov_b32_e32 v122, v2
	v_mov_b32_e32 v123, v2
	v_mov_b32_e32 v124, v2
	v_mov_b32_e32 v125, v2
	v_mov_b32_e32 v126, v2
	v_mov_b32_e32 v127, v2
	v_mov_b32_e32 v128, v2
	v_mov_b32_e32 v129, v2
	s_nop 0
	s_nop 0
